# v40 + non-leader workgroups issue their agent-scope L1 invalidate at barrier arrival (overlapped with the wait) instead of after the release; leaders unchanged
# speedup vs baseline: 1.0024x; 1.0024x over previous
; __device__ __forceinline__ unsigned xb_ld(unsigned* p)              { return __hip_atomic_load(p, __ATOMIC_RELAXED, __HIP_MEMORY_SCOPE_AGENT); }
; __device__ __forceinline__ unsigned xb_add(unsigned* p, unsigned v) { return __hip_atomic_fetch_add(p, v, __ATOMIC_RELAXED, __HIP_MEMORY_SCOPE_AGENT); }
; #define XB_SPIN(cond, bar) do { unsigned _sp = 0; while (cond) { __builtin_amdgcn_s_sleep(1); \
;     if ((++_sp & 255u) == 0u) { if (xb_ld(&(bar)[XB_TMO])) break; if (_sp > XB_SPIN_CAP) { atomicAdd(&(bar)[XB_TMO], 1u); break; } } } } while (0)
; __device__ __forceinline__ void xcd_barrier(unsigned* bar, volatile LAS unsigned* st) {
;     ...
;         const unsigned old = xb_add(&bar[XB_XSUB(x)], 1u);
;         const unsigned gen = old / nloc;
;         if (old + 1u == (gen + 1u) * nloc) {
;     ...
;         } else {
;             XB_SPIN(xb_ld(&bar[XB_XGEN(x)]) == gen, bar);
.LBB0_498:
	s_or_b64 exec, exec, s[8:9]
	v_cvt_f32_u32_e32 v5, v3
	s_waitcnt vmcnt(0)
	v_readfirstlane_b32 s6, v4
	v_sub_u32_e32 v4, 0, v3
	v_rcp_iflag_f32_e32 v5, v5
	v_add_u32_e32 v6, s6, v0
	v_mul_f32_e32 v5, 0x4f7ffffe, v5
	v_cvt_u32_f32_e32 v5, v5
	v_mul_lo_u32 v0, v4, v5
	v_mul_hi_u32 v0, v5, v0
	v_add_u32_e32 v0, v5, v0
	v_mul_hi_u32 v0, v6, v0
	v_mul_lo_u32 v4, v0, v3
	v_sub_u32_e32 v4, v6, v4
	v_add_u32_e32 v5, 1, v0
	v_cmp_ge_u32_e32 vcc, v4, v3
	s_nop 1
	v_cndmask_b32_e32 v0, v0, v5, vcc
	v_sub_u32_e32 v5, v4, v3
	v_cndmask_b32_e32 v4, v4, v5, vcc
	v_add_u32_e32 v5, 1, v0
	v_cmp_ge_u32_e32 vcc, v4, v3
	v_add_u32_e32 v4, 1, v6
	s_nop 0
	v_cndmask_b32_e32 v0, v0, v5, vcc
	v_mul_lo_u32 v5, v3, v0
	v_add_u32_e32 v3, v5, v3
	v_cmp_ne_u32_e32 vcc, v4, v3
	s_and_saveexec_b64 s[6:7], vcc
	s_xor_b64 s[6:7], exec, s[6:7]
	s_cbranch_execz .LBB0_512
	s_waitcnt lgkmcnt(0)
	buffer_inv sc1
	global_load_dword v2, v235, s[4:5] offset:1024 sc1
	s_add_u32 s12, s4, 0x2400
	s_addc_u32 s13, s5, 0
	s_waitcnt vmcnt(0)
	v_cmp_eq_u32_e32 vcc, v2, v0
	s_and_saveexec_b64 s[8:9], vcc
	s_cbranch_execz .LBB0_511
	s_add_u32 s10, s42, 0x31046200
	s_addc_u32 s11, s43, 0
	s_mov_b32 s14, 1
	s_mov_b64 s[16:17], 0
	s_branch .LBB0_502

; __device__ __forceinline__ unsigned xb_ld(unsigned* p)              { return __hip_atomic_load(p, __ATOMIC_RELAXED, __HIP_MEMORY_SCOPE_AGENT); }
; #define XB_SPIN(cond, bar) do { unsigned _sp = 0; while (cond) { __builtin_amdgcn_s_sleep(1); \
;     if ((++_sp & 255u) == 0u) { if (xb_ld(&(bar)[XB_TMO])) break; if (_sp > XB_SPIN_CAP) { atomicAdd(&(bar)[XB_TMO], 1u); break; } } } } while (0)
; __device__ __forceinline__ void xcd_barrier(unsigned* bar, volatile LAS unsigned* st) {
;     ...
;             XB_SPIN(xb_ld(&bar[XB_XGEN(x)]) == gen, bar);
;             __builtin_amdgcn_fence(__ATOMIC_ACQUIRE, "agent");
;             asm volatile("s_waitcnt vmcnt(0)" ::: "memory");
.LBB0_511:
	s_or_b64 exec, exec, s[8:9]
	s_waitcnt vmcnt(0)
	s_waitcnt vmcnt(0)
